# v3 + sample GEMMs of the Q / O / mixer-output projections rescheduled by hand (all fragment loads in flight at once, batched partial reads) + GEMM tail drains counted
# speedup vs baseline: 1.0148x; 1.0100x over previous
; #define PG8_WAIT_V(n) asm volatile("s_waitcnt vmcnt(" #n ")" ::: "memory")
; #define PG8_BAR __builtin_amdgcn_s_barrier()
; template <class Epi, class Sched, bool ALIGN_EPI = false, bool SP2 = false>
; __device__ __forceinline__ void gemm_phase(PG8_LAS unsigned char* lds, const Gemm g, const Sched& S, const Epi& E, const int wave_id) {
;     ...
;     PG8_WAIT_V(0);
;     if constexpr (!ALIGN_EPI) { if (wr == 0) PG8_BAR; }
;     PG8_BAR;
.LBB0_1740:
	s_waitcnt vmcnt(12)
	s_barrier

; #define LAS __attribute__((address_space(3)))
; #define LDS_BARRIER() asm volatile("s_waitcnt lgkmcnt(0)\n\ts_barrier" ::: "memory")
; #define MFMA16(a, b, c) __builtin_amdgcn_mfma_f32_16x16x32_bf16((a), (b), (c), 0, 0, 0)
; template <class Epi, int N>
; __device__ __forceinline__ void sgemm16(Frame& F0, const bf16_t* A, const bf16_t* Bt, int K, const Epi& E) {
;     ...
;         const bf16_t* ap = A16 + (size_t)fr * K + ksi * kslice + 8 * fq;
;         const bf16_t* bp = Bt + (size_t)(slot * CW + (ng * NTW) * 16 + fr) * K + ksi * kslice + 8 * fq;
;         {
;             bf16x8 Af[2][4], Bf[2][4][NTW];
;     ...
;             SG_LOAD(0, 0);
;             for (int kb = 0; kb < nkb; kb += 2) {
;                 if (kb + 1 < nkb) SG_LOAD(kb + 1, 1);
; #pragma unroll
;                 for (int k4 = 0; k4 < 4; ++k4)
; #pragma unroll
;                     for (int jn = 0; jn < NTW; ++jn) acc[jn] = MFMA16(Bf[0][k4][jn], Af[0][k4], acc[jn]);
;                 if (kb + 1 < nkb) {
;                     if (kb + 2 < nkb) SG_LOAD(kb + 2, 0);
; #pragma unroll
;                     for (int k4 = 0; k4 < 4; ++k4)
; #pragma unroll
;                         for (int jn = 0; jn < NTW; ++jn) acc[jn] = MFMA16(Bf[1][k4][jn], Af[1][k4], acc[jn]);
;                 }
;             }
;     ...
;         }
; #pragma unroll
;         for (int jn = 0; jn < NTW; ++jn) *(LAS f32x4*)(lds + ((size_t)((ksi * 16 + fr) * CW + (ng * NTW + jn) * 16 + 4 * fq)) * 4) = acc[jn];
;         LDS_BARRIER();
;         if (eact) {
;             f32x4 s0 = (f32x4){0.f, 0.f, 0.f, 0.f}, s1 = s0;
; #pragma unroll
;             for (int kk = 0; kk < KS; ++kk) { const LAS f32x4* p = (const LAS f32x4*)(lds + ((size_t)((kk * 16 + erow) * CW + 8 * ecg)) * 4); s0 += p[0]; s1 += p[1]; }
;             E(16 * F.xq + erow, slot, slot * CW + 8 * ecg, s0, s1, pre);
;         }
;         LDS_BARRIER();
;     __device__ __forceinline__ void operator()(int row, int strip, int col, f32x4 s0, f32x4 s1, const Pre& pr) const {
;         float* p = xs + (size_t)row * D + col; const f32x4 o0 = pr.x0 + s0, o1 = pr.x1 + s1;
;         *(f32x4*)p = o0; *(f32x4*)(p + 4) = o1; *(u32x4*)(xb + (size_t)row * D + col) = pack8(o0, o1);
;         const int ln = ((row & 15) << 2) | ((col >> 3) & 3);
;         float ss = dot4(o0, o0) + dot4(o1, o1); ss += shx(ss, 1, ln); ss += shx(ss, 2, ln);
;         if ((col & 31) == 0) rsqs[row * 32 + strip] = ss;
;     }
.LBB0_1746:
	s_or_b64 exec, exec, s[2:3]
	v_add_u32_e32 v30, v23, v25
	v_ashrrev_i32_e32 v31, 31, v30
	v_lshlrev_b64 v[30:31], 12, v[30:31]
	v_lshl_add_u64 v[54:55], v[10:11], 0, v[30:31]
	s_mov_b32 s2, 0x10000
	v_add_co_u32_e32 v56, vcc, s2, v54
	global_load_dwordx4 v[62:65], v[8:9], off
	global_load_dwordx4 v[94:97], v[54:55], off
	v_addc_co_u32_e32 v57, vcc, 0, v55, vcc
	global_load_dwordx4 v[126:129], v[56:57], off
	global_load_dwordx4 v[98:101], v[54:55], off offset:64
	global_load_dwordx4 v[66:69], v[8:9], off offset:64
	global_load_dwordx4 v[130:133], v[56:57], off offset:64
	global_load_dwordx4 v[102:105], v[54:55], off offset:128
	global_load_dwordx4 v[70:73], v[8:9], off offset:128
	global_load_dwordx4 v[134:137], v[56:57], off offset:128
	global_load_dwordx4 v[106:109], v[54:55], off offset:192
	global_load_dwordx4 v[74:77], v[8:9], off offset:192
	global_load_dwordx4 v[138:141], v[56:57], off offset:192
	global_load_dwordx4 v[110:113], v[54:55], off offset:256
	global_load_dwordx4 v[78:81], v[8:9], off offset:256
	global_load_dwordx4 v[142:145], v[56:57], off offset:256
	global_load_dwordx4 v[114:117], v[54:55], off offset:320
	global_load_dwordx4 v[82:85], v[8:9], off offset:320
	global_load_dwordx4 v[146:149], v[56:57], off offset:320
	global_load_dwordx4 v[118:121], v[54:55], off offset:384
	global_load_dwordx4 v[86:89], v[8:9], off offset:384
	global_load_dwordx4 v[150:153], v[56:57], off offset:384
	global_load_dwordx4 v[122:125], v[54:55], off offset:448
	global_load_dwordx4 v[90:93], v[8:9], off offset:448
	global_load_dwordx4 v[154:157], v[56:57], off offset:448
	s_waitcnt vmcnt(0)
	v_mfma_f32_16x16x32_bf16 v[34:37], v[94:97], v[62:65], 0
	v_mfma_f32_16x16x32_bf16 v[30:33], v[126:129], v[62:65], 0
	v_mfma_f32_16x16x32_bf16 v[34:37], v[98:101], v[66:69], v[34:37]
	v_mfma_f32_16x16x32_bf16 v[30:33], v[130:133], v[66:69], v[30:33]
	v_mfma_f32_16x16x32_bf16 v[34:37], v[102:105], v[70:73], v[34:37]
	v_mfma_f32_16x16x32_bf16 v[30:33], v[134:137], v[70:73], v[30:33]
	v_mfma_f32_16x16x32_bf16 v[34:37], v[106:109], v[74:77], v[34:37]
	v_mfma_f32_16x16x32_bf16 v[30:33], v[138:141], v[74:77], v[30:33]
	v_mfma_f32_16x16x32_bf16 v[34:37], v[110:113], v[78:81], v[34:37]
	v_mfma_f32_16x16x32_bf16 v[30:33], v[142:145], v[78:81], v[30:33]
	v_mfma_f32_16x16x32_bf16 v[34:37], v[114:117], v[82:85], v[34:37]
	v_mfma_f32_16x16x32_bf16 v[30:33], v[146:149], v[82:85], v[30:33]
	v_mfma_f32_16x16x32_bf16 v[34:37], v[118:121], v[86:89], v[34:37]
	v_mfma_f32_16x16x32_bf16 v[30:33], v[150:153], v[86:89], v[30:33]
	v_mfma_f32_16x16x32_bf16 v[34:37], v[122:125], v[90:93], v[34:37]
	v_mfma_f32_16x16x32_bf16 v[30:33], v[154:157], v[90:93], v[30:33]
	s_nop 7
	ds_write_b128 v27, v[34:37]
	s_nop 1
	ds_write_b128 v27, v[30:33] offset:64
	s_waitcnt lgkmcnt(0)
	s_barrier
	s_and_saveexec_b64 s[2:3], s[4:5]
	s_cbranch_execz .LBB0_1743
	ds_read_b128 v[62:65], v28
	ds_read_b128 v[66:69], v28 offset:16
	ds_read_b128 v[70:73], v28 offset:2048
	ds_read_b128 v[74:77], v28 offset:2064
	ds_read_b128 v[78:81], v28 offset:4096
	ds_read_b128 v[82:85], v28 offset:4112
	ds_read_b128 v[86:89], v28 offset:6144
	ds_read_b128 v[90:93], v28 offset:6160
	ds_read_b128 v[94:97], v28 offset:8192
	ds_read_b128 v[98:101], v28 offset:8208
	ds_read_b128 v[102:105], v28 offset:10240
	ds_read_b128 v[106:109], v28 offset:10256
	ds_read_b128 v[110:113], v28 offset:12288
	ds_read_b128 v[114:117], v28 offset:12304
	ds_read_b128 v[118:121], v28 offset:14336
	ds_read_b128 v[122:125], v28 offset:14352
	s_waitcnt lgkmcnt(0)
	v_pk_add_f32 v[38:39], v[64:65], 0 op_sel_hi:[1,0]
	v_pk_add_f32 v[40:41], v[62:63], 0 op_sel_hi:[1,0]
	v_pk_add_f32 v[36:37], v[68:69], 0 op_sel_hi:[1,0]
	v_pk_add_f32 v[34:35], v[66:67], 0 op_sel_hi:[1,0]
	v_pk_add_f32 v[38:39], v[38:39], v[72:73]
	v_pk_add_f32 v[40:41], v[40:41], v[70:71]
	v_pk_add_f32 v[36:37], v[36:37], v[76:77]
	v_pk_add_f32 v[34:35], v[34:35], v[74:75]
	v_pk_add_f32 v[38:39], v[38:39], v[80:81]
	v_pk_add_f32 v[40:41], v[40:41], v[78:79]
	v_pk_add_f32 v[36:37], v[36:37], v[84:85]
	v_pk_add_f32 v[34:35], v[34:35], v[82:83]
	v_pk_add_f32 v[38:39], v[38:39], v[88:89]
	v_pk_add_f32 v[40:41], v[40:41], v[86:87]
	v_pk_add_f32 v[36:37], v[36:37], v[92:93]
	v_pk_add_f32 v[34:35], v[34:35], v[90:91]
	v_pk_add_f32 v[38:39], v[38:39], v[96:97]
	v_pk_add_f32 v[40:41], v[40:41], v[94:95]
	v_pk_add_f32 v[36:37], v[36:37], v[100:101]
	v_pk_add_f32 v[34:35], v[34:35], v[98:99]
	v_pk_add_f32 v[38:39], v[38:39], v[104:105]
	v_pk_add_f32 v[40:41], v[40:41], v[102:103]
	v_pk_add_f32 v[36:37], v[36:37], v[108:109]
	v_pk_add_f32 v[34:35], v[34:35], v[106:107]
	v_pk_add_f32 v[38:39], v[38:39], v[112:113]
	v_pk_add_f32 v[40:41], v[40:41], v[110:111]
	v_pk_add_f32 v[36:37], v[36:37], v[116:117]
	v_pk_add_f32 v[34:35], v[34:35], v[114:115]
	v_pk_add_f32 v[38:39], v[38:39], v[120:121]
	v_pk_add_f32 v[40:41], v[40:41], v[118:119]
	v_pk_add_f32 v[6:7], v[6:7], v[38:39]
	v_pk_add_f32 v[4:5], v[4:5], v[40:41]
	v_pk_add_f32 v[30:31], v[34:35], v[122:123]
	v_pk_add_f32 v[32:33], v[36:37], v[124:125]
	v_lshl_add_u64 v[34:35], v[16:17], 2, v[12:13]
	v_pk_add_f32 v[0:1], v[0:1], v[30:31]
	v_pk_add_f32 v[2:3], v[2:3], v[32:33]
	global_store_dwordx4 v[34:35], v[4:7], off
	global_store_dwordx4 v[34:35], v[0:3], off offset:16
	v_cvt_pk_bf16_f32 v30, v4, v5
	v_cvt_pk_bf16_f32 v32, v0, v1
	v_mul_f32_e32 v5, v5, v5
	v_mul_f32_e32 v1, v1, v1
	v_fmac_f32_e32 v5, v4, v4
	v_mul_f32_e32 v4, v7, v7
	v_fmac_f32_e32 v1, v0, v0
	v_mul_f32_e32 v0, v3, v3
	v_fmac_f32_e32 v4, v6, v6
	v_fmac_f32_e32 v0, v2, v2
	v_add_f32_e32 v4, v5, v4
	v_add_f32_e32 v0, v1, v0
	v_add_f32_e32 v0, v4, v0
	ds_bpermute_b32 v1, v20, v0
	v_cvt_pk_bf16_f32 v31, v6, v7
	v_cvt_pk_bf16_f32 v33, v2, v3
	v_lshl_add_u64 v[16:17], v[16:17], 1, v[14:15]
	global_store_dwordx4 v[16:17], v[30:33], off
	s_waitcnt lgkmcnt(0)
	v_add_f32_e32 v0, v0, v1
	ds_bpermute_b32 v1, v21, v0
	s_and_b64 exec, exec, s[6:7]
	s_cbranch_execz .LBB0_1743
	v_add_u32_e32 v2, v22, v26
	v_ashrrev_i32_e32 v3, 31, v2
	v_lshl_add_u64 v[2:3], v[2:3], 2, s[10:11]
	s_waitcnt lgkmcnt(0)
	v_add_f32_e32 v0, v0, v1
	global_store_dword v[2:3], v0, off
	s_branch .LBB0_1743

; #define LAS __attribute__((address_space(3)))
; #define LDS_BARRIER() asm volatile("s_waitcnt lgkmcnt(0)\n\ts_barrier" ::: "memory")
; #define MFMA16(a, b, c) __builtin_amdgcn_mfma_f32_16x16x32_bf16((a), (b), (c), 0, 0, 0)
;     __device__ __forceinline__ Pre pre(int row, int col) const { return Pre{rstd32(rsqs + row * 32)}; }
; template <class Epi, int N>
; __device__ __forceinline__ void sgemm16(Frame& F0, const bf16_t* A, const bf16_t* Bt, int K, const Epi& E) {
;     ...
;         const int erow = tid / (CW / 8), ecg = tid % (CW / 8); const bool eact = tid < 2 * CW;
;         typename Epi::Pre pre{};
;         if (eact) pre = E.pre(16 * F.xq + erow, slot * CW + 8 * ecg);
;         f32x4 acc[NTW];
; #pragma unroll
;         for (int jn = 0; jn < NTW; ++jn) acc[jn] = (f32x4){0.f, 0.f, 0.f, 0.f};
;         const bf16_t* ap = A16 + (size_t)fr * K + ksi * kslice + 8 * fq;
;         const bf16_t* bp = Bt + (size_t)(slot * CW + (ng * NTW) * 16 + fr) * K + ksi * kslice + 8 * fq;
;         {
;             bf16x8 Af[2][4], Bf[2][4][NTW];
;     ...
;             SG_LOAD(0, 0);
;             for (int kb = 0; kb < nkb; kb += 2) {
;                 if (kb + 1 < nkb) SG_LOAD(kb + 1, 1);
; #pragma unroll
;                 for (int k4 = 0; k4 < 4; ++k4)
; #pragma unroll
;                     for (int jn = 0; jn < NTW; ++jn) acc[jn] = MFMA16(Bf[0][k4][jn], Af[0][k4], acc[jn]);
;                 if (kb + 1 < nkb) {
;                     if (kb + 2 < nkb) SG_LOAD(kb + 2, 0);
; #pragma unroll
;                     for (int k4 = 0; k4 < 4; ++k4)
; #pragma unroll
;                         for (int jn = 0; jn < NTW; ++jn) acc[jn] = MFMA16(Bf[1][k4][jn], Af[1][k4], acc[jn]);
;                 }
;             }
;     ...
;         }
; #pragma unroll
;         for (int jn = 0; jn < NTW; ++jn) *(LAS f32x4*)(lds + ((size_t)((ksi * 16 + fr) * CW + (ng * NTW + jn) * 16 + 4 * fq)) * 4) = acc[jn];
;         LDS_BARRIER();
;         if (eact) {
;             f32x4 s0 = (f32x4){0.f, 0.f, 0.f, 0.f}, s1 = s0;
; #pragma unroll
;             for (int kk = 0; kk < KS; ++kk) { const LAS f32x4* p = (const LAS f32x4*)(lds + ((size_t)((kk * 16 + erow) * CW + 8 * ecg)) * 4); s0 += p[0]; s1 += p[1]; }
;             E(16 * F.xq + erow, slot, slot * CW + 8 * ecg, s0, s1, pre);
;         }
;         LDS_BARRIER();
;     __device__ __forceinline__ Pre pre(int row, int col) const { return Pre{rstd32(rsqs + row * 32)}; }
.LBB0_1905:
	v_mov_b32_e32 v8, 0
	s_and_saveexec_b64 s[2:3], s[4:5]
	s_cbranch_execz .Lsq_l0
	global_load_dwordx4 v[18:21], v[0:1], off offset:48
	global_load_dwordx4 v[22:25], v[0:1], off offset:32
	global_load_dwordx4 v[26:29], v[0:1], off
	global_load_dwordx4 v[30:33], v[0:1], off offset:16
	global_load_dwordx4 v[58:61], v[0:1], off offset:112
	global_load_dwordx4 v[54:57], v[0:1], off offset:96
	global_load_dwordx4 v[50:53], v[0:1], off offset:80
	global_load_dwordx4 v[46:49], v[0:1], off offset:64
	.Lsq_l0:
	s_or_b64 exec, exec, s[2:3]
	v_add_u32_e32 v38, v12, v13
	v_ashrrev_i32_e32 v39, 31, v38
	v_lshlrev_b64 v[38:39], 11, v[38:39]
	v_lshl_add_u64 v[42:43], v[4:5], 0, v[38:39]
	v_add_co_u32_e32 v44, vcc, 0x8000, v42
	global_load_dwordx4 v[62:65], v[2:3], off
	global_load_dwordx4 v[78:81], v[42:43], off
	v_addc_co_u32_e32 v45, vcc, 0, v43, vcc
	global_load_dwordx4 v[94:97], v[44:45], off
	global_load_dwordx4 v[82:85], v[42:43], off offset:64
	global_load_dwordx4 v[66:69], v[2:3], off offset:64
	global_load_dwordx4 v[98:101], v[44:45], off offset:64
	global_load_dwordx4 v[86:89], v[42:43], off offset:128
	global_load_dwordx4 v[70:73], v[2:3], off offset:128
	global_load_dwordx4 v[102:105], v[44:45], off offset:128
	global_load_dwordx4 v[90:93], v[42:43], off offset:192
	global_load_dwordx4 v[74:77], v[2:3], off offset:192
	global_load_dwordx4 v[106:109], v[44:45], off offset:192
	s_waitcnt vmcnt(0)
	s_and_saveexec_b64 s[2:3], s[4:5]
	s_cbranch_execz .Lsq_l1
	v_mov_b32_e32 v17, 0x358637bd
	s_mov_b32 s6, 0x800000
	v_pk_add_f32 v[28:29], v[28:29], v[32:33]
	v_pk_add_f32 v[26:27], v[26:27], v[30:31]
	v_pk_add_f32 v[24:25], v[28:29], v[24:25]
	v_pk_add_f32 v[22:23], v[26:27], v[22:23]
	v_pk_add_f32 v[34:35], v[24:25], v[20:21]
	v_pk_add_f32 v[36:37], v[22:23], v[18:19]
	v_pk_add_f32 v[32:33], v[34:35], v[48:49]
	v_pk_add_f32 v[30:31], v[36:37], v[46:47]
	v_pk_add_f32 v[28:29], v[32:33], v[52:53]
	v_pk_add_f32 v[26:27], v[30:31], v[50:51]
	v_pk_add_f32 v[24:25], v[28:29], v[56:57]
	v_pk_add_f32 v[22:23], v[26:27], v[54:55]
	v_pk_add_f32 v[20:21], v[24:25], v[60:61]
	v_pk_add_f32 v[18:19], v[22:23], v[58:59]
	s_nop 0
	v_pk_mov_b32 v[22:23], v[18:19], v[20:21] op_sel:[1,0]
	v_mov_b32_e32 v19, v21
	v_pk_add_f32 v[18:19], v[22:23], v[18:19]
	s_nop 0
	v_add_f32_e32 v8, v18, v19
	v_fmamk_f32 v8, v8, 0x3a800000, v17
	v_cmp_gt_f32_e32 vcc, s6, v8
	v_mul_f32_e32 v17, 0x4b800000, v8
	s_nop 0
	v_cndmask_b32_e32 v8, v8, v17, vcc
	v_rsq_f32_e32 v8, v8
	s_nop 0
	v_mul_f32_e32 v17, 0x45800000, v8
	v_cndmask_b32_e32 v8, v8, v17, vcc
	.Lsq_l1:
	s_or_b64 exec, exec, s[2:3]
	s_nop 1
	v_mfma_f32_16x16x32_bf16 v[22:25], v[78:81], v[62:65], 0
	v_mfma_f32_16x16x32_bf16 v[18:21], v[94:97], v[62:65], 0
	v_mfma_f32_16x16x32_bf16 v[22:25], v[82:85], v[66:69], v[22:25]
	v_mfma_f32_16x16x32_bf16 v[22:25], v[86:89], v[70:73], v[22:25]
	v_mfma_f32_16x16x32_bf16 v[18:21], v[98:101], v[66:69], v[18:21]
	v_mfma_f32_16x16x32_bf16 v[18:21], v[102:105], v[70:73], v[18:21]
	v_mfma_f32_16x16x32_bf16 v[22:25], v[90:93], v[74:77], v[22:25]
	v_mfma_f32_16x16x32_bf16 v[18:21], v[106:109], v[74:77], v[18:21]
	s_nop 7
	ds_write_b128 v15, v[22:25]
	s_nop 1
	ds_write_b128 v15, v[18:21] offset:64
	s_waitcnt lgkmcnt(0)
	s_barrier
	s_and_saveexec_b64 s[2:3], s[4:5]
	s_cbranch_execz .LBB0_1904
	ds_read_b128 v[46:49], v16
	ds_read_b128 v[50:53], v16 offset:16
	ds_read_b128 v[54:57], v16 offset:2048
	ds_read_b128 v[58:61], v16 offset:2064
	ds_read_b128 v[62:65], v16 offset:4096
	ds_read_b128 v[66:69], v16 offset:4112
	ds_read_b128 v[70:73], v16 offset:6144
	ds_read_b128 v[74:77], v16 offset:6160
	ds_read_b128 v[78:81], v16 offset:8192
	ds_read_b128 v[82:85], v16 offset:8208
	ds_read_b128 v[86:89], v16 offset:10240
	ds_read_b128 v[90:93], v16 offset:10256
	ds_read_b128 v[94:97], v16 offset:12288
	ds_read_b128 v[98:101], v16 offset:12304
	ds_read_b128 v[102:105], v16 offset:14336
	ds_read_b128 v[106:109], v16 offset:14352
	s_waitcnt lgkmcnt(0)
	v_pk_add_f32 v[26:27], v[48:49], 0 op_sel_hi:[1,0]
	v_pk_add_f32 v[28:29], v[46:47], 0 op_sel_hi:[1,0]
	v_pk_add_f32 v[24:25], v[52:53], 0 op_sel_hi:[1,0]
	v_pk_add_f32 v[22:23], v[50:51], 0 op_sel_hi:[1,0]
	v_pk_add_f32 v[26:27], v[26:27], v[56:57]
	v_pk_add_f32 v[28:29], v[28:29], v[54:55]
	v_pk_add_f32 v[24:25], v[24:25], v[60:61]
	v_pk_add_f32 v[22:23], v[22:23], v[58:59]
	v_pk_add_f32 v[26:27], v[26:27], v[64:65]
	v_pk_add_f32 v[28:29], v[28:29], v[62:63]
	v_pk_add_f32 v[24:25], v[24:25], v[68:69]
	v_pk_add_f32 v[22:23], v[22:23], v[66:67]
	v_pk_add_f32 v[26:27], v[26:27], v[72:73]
	v_pk_add_f32 v[28:29], v[28:29], v[70:71]
	v_pk_add_f32 v[24:25], v[24:25], v[76:77]
	v_pk_add_f32 v[22:23], v[22:23], v[74:75]
	v_pk_add_f32 v[26:27], v[26:27], v[80:81]
	v_pk_add_f32 v[28:29], v[28:29], v[78:79]
	v_pk_add_f32 v[24:25], v[24:25], v[84:85]
	v_pk_add_f32 v[22:23], v[22:23], v[82:83]
	v_pk_add_f32 v[26:27], v[26:27], v[88:89]
	v_pk_add_f32 v[28:29], v[28:29], v[86:87]
	v_pk_add_f32 v[24:25], v[24:25], v[92:93]
	v_pk_add_f32 v[22:23], v[22:23], v[90:91]
	v_pk_add_f32 v[26:27], v[26:27], v[96:97]
	v_pk_add_f32 v[28:29], v[28:29], v[94:95]
	v_pk_add_f32 v[24:25], v[24:25], v[100:101]
	v_pk_add_f32 v[22:23], v[22:23], v[98:99]
	v_pk_add_f32 v[26:27], v[26:27], v[104:105]
	v_pk_add_f32 v[28:29], v[28:29], v[102:103]
	v_pk_add_f32 v[24:25], v[24:25], v[108:109]
	v_pk_add_f32 v[22:23], v[22:23], v[106:107]
	v_add_u32_e32 v18, v10, v13
	v_ashrrev_i32_e32 v19, 31, v18
	v_lshl_add_u64 v[30:31], v[18:19], 2, v[6:7]
	v_pk_mul_f32 v[20:21], v[8:9], v[26:27] op_sel_hi:[0,1]
	v_pk_mul_f32 v[18:19], v[8:9], v[28:29] op_sel_hi:[0,1]
	global_store_dwordx4 v[30:31], v[18:21], off
	s_nop 1
	v_pk_mul_f32 v[20:21], v[8:9], v[24:25] op_sel_hi:[0,1]
	v_pk_mul_f32 v[18:19], v[8:9], v[22:23] op_sel_hi:[0,1]
	global_store_dwordx4 v[30:31], v[18:21], off offset:16
	s_branch .LBB0_1904

; #define LAS __attribute__((address_space(3)))
; #define LDS_BARRIER() asm volatile("s_waitcnt lgkmcnt(0)\n\ts_barrier" ::: "memory")
; #define MFMA16(a, b, c) __builtin_amdgcn_mfma_f32_16x16x32_bf16((a), (b), (c), 0, 0, 0)
; #define SG_LOAD(kb_, buf_) do { _Pragma("unroll") for (int k4 = 0; k4 < 4; ++k4) { Af[buf_][k4] = *(const bf16x8*)(ap + 128 * (kb_) + 32 * k4); \
;                 _Pragma("unroll") for (int jn = 0; jn < NTW; ++jn) Bf[buf_][k4][jn] = *(const bf16x8*)(bp + (size_t)(16 * jn) * K + 128 * (kb_) + 32 * k4); } } while (0)
;     __device__ __forceinline__ Pre pre(int row, int col) const { return Pre{rstd32(rsqs + row * 32)}; }
;     __device__ __forceinline__ Pre pre(int row, int col) const { return Pre{rstd32(rsqs + row * 32)}; }
; template <class Epi, int N>
; __device__ __forceinline__ void sgemm16(Frame& F0, const bf16_t* A, const bf16_t* Bt, int K, const Epi& E) {
;     ...
;         const bf16_t* ap = A16 + (size_t)fr * K + ksi * kslice + 8 * fq;
;         const bf16_t* bp = Bt + (size_t)(slot * CW + (ng * NTW) * 16 + fr) * K + ksi * kslice + 8 * fq;
;         {
;             bf16x8 Af[2][4], Bf[2][4][NTW];
;     ...
;             SG_LOAD(0, 0);
;             for (int kb = 0; kb < nkb; kb += 2) {
;                 if (kb + 1 < nkb) SG_LOAD(kb + 1, 1);
; #pragma unroll
;                 for (int k4 = 0; k4 < 4; ++k4)
; #pragma unroll
;                     for (int jn = 0; jn < NTW; ++jn) acc[jn] = MFMA16(Bf[0][k4][jn], Af[0][k4], acc[jn]);
;                 if (kb + 1 < nkb) {
;                     if (kb + 2 < nkb) SG_LOAD(kb + 2, 0);
; #pragma unroll
;                     for (int k4 = 0; k4 < 4; ++k4)
; #pragma unroll
;                         for (int jn = 0; jn < NTW; ++jn) acc[jn] = MFMA16(Bf[1][k4][jn], Af[1][k4], acc[jn]);
;                 }
;             }
;     ...
;         }
; #pragma unroll
;         for (int jn = 0; jn < NTW; ++jn) *(LAS f32x4*)(lds + ((size_t)((ksi * 16 + fr) * CW + (ng * NTW + jn) * 16 + 4 * fq)) * 4) = acc[jn];
;         LDS_BARRIER();
;         if (eact) {
;             f32x4 s0 = (f32x4){0.f, 0.f, 0.f, 0.f}, s1 = s0;
; #pragma unroll
;             for (int kk = 0; kk < KS; ++kk) { const LAS f32x4* p = (const LAS f32x4*)(lds + ((size_t)((kk * 16 + erow) * CW + 8 * ecg)) * 4); s0 += p[0]; s1 += p[1]; }
;             E(16 * F.xq + erow, slot, slot * CW + 8 * ecg, s0, s1, pre);
;         }
;         LDS_BARRIER();
.LBB0_2265:
	s_or_b64 exec, exec, s[2:3]
	v_add_u32_e32 v30, v23, v25
	v_ashrrev_i32_e32 v31, 31, v30
	v_lshlrev_b64 v[30:31], 11, v[30:31]
	v_lshl_add_u64 v[54:55], v[10:11], 0, v[30:31]
	s_mov_b32 s2, 0x8000
	v_add_co_u32_e32 v56, vcc, s2, v54
	global_load_dwordx4 v[62:65], v[8:9], off
	global_load_dwordx4 v[78:81], v[54:55], off
	v_addc_co_u32_e32 v57, vcc, 0, v55, vcc
	global_load_dwordx4 v[94:97], v[56:57], off
	global_load_dwordx4 v[82:85], v[54:55], off offset:64
	global_load_dwordx4 v[66:69], v[8:9], off offset:64
	global_load_dwordx4 v[98:101], v[56:57], off offset:64
	global_load_dwordx4 v[86:89], v[54:55], off offset:128
	global_load_dwordx4 v[70:73], v[8:9], off offset:128
	global_load_dwordx4 v[102:105], v[56:57], off offset:128
	global_load_dwordx4 v[90:93], v[54:55], off offset:192
	global_load_dwordx4 v[74:77], v[8:9], off offset:192
	global_load_dwordx4 v[106:109], v[56:57], off offset:192
	s_waitcnt vmcnt(0)
	v_mfma_f32_16x16x32_bf16 v[34:37], v[78:81], v[62:65], 0
	v_mfma_f32_16x16x32_bf16 v[30:33], v[94:97], v[62:65], 0
	v_mfma_f32_16x16x32_bf16 v[34:37], v[82:85], v[66:69], v[34:37]
	v_mfma_f32_16x16x32_bf16 v[30:33], v[98:101], v[66:69], v[30:33]
	v_mfma_f32_16x16x32_bf16 v[34:37], v[86:89], v[70:73], v[34:37]
	v_mfma_f32_16x16x32_bf16 v[30:33], v[102:105], v[70:73], v[30:33]
	v_mfma_f32_16x16x32_bf16 v[34:37], v[90:93], v[74:77], v[34:37]
	v_mfma_f32_16x16x32_bf16 v[30:33], v[106:109], v[74:77], v[30:33]
	s_nop 7
	ds_write_b128 v27, v[34:37]
	s_nop 1
	ds_write_b128 v27, v[30:33] offset:64
	s_waitcnt lgkmcnt(0)
	s_barrier
	s_and_saveexec_b64 s[2:3], s[4:5]
	s_cbranch_execz .LBB0_2262
	ds_read_b128 v[62:65], v28
	ds_read_b128 v[66:69], v28 offset:16
	ds_read_b128 v[70:73], v28 offset:2048
	ds_read_b128 v[74:77], v28 offset:2064
	ds_read_b128 v[78:81], v28 offset:4096
	ds_read_b128 v[82:85], v28 offset:4112
	ds_read_b128 v[86:89], v28 offset:6144
	ds_read_b128 v[90:93], v28 offset:6160
	ds_read_b128 v[94:97], v28 offset:8192
	ds_read_b128 v[98:101], v28 offset:8208
	ds_read_b128 v[102:105], v28 offset:10240
	ds_read_b128 v[106:109], v28 offset:10256
	ds_read_b128 v[110:113], v28 offset:12288
	ds_read_b128 v[114:117], v28 offset:12304
	ds_read_b128 v[118:121], v28 offset:14336
	ds_read_b128 v[122:125], v28 offset:14352
	s_waitcnt lgkmcnt(0)
	v_pk_add_f32 v[38:39], v[64:65], 0 op_sel_hi:[1,0]
	v_pk_add_f32 v[40:41], v[62:63], 0 op_sel_hi:[1,0]
	v_pk_add_f32 v[36:37], v[68:69], 0 op_sel_hi:[1,0]
	v_pk_add_f32 v[34:35], v[66:67], 0 op_sel_hi:[1,0]
	v_pk_add_f32 v[38:39], v[38:39], v[72:73]
	v_pk_add_f32 v[40:41], v[40:41], v[70:71]
	v_pk_add_f32 v[36:37], v[36:37], v[76:77]
	v_pk_add_f32 v[34:35], v[34:35], v[74:75]
	v_pk_add_f32 v[38:39], v[38:39], v[80:81]
	v_pk_add_f32 v[40:41], v[40:41], v[78:79]
	v_pk_add_f32 v[36:37], v[36:37], v[84:85]
	v_pk_add_f32 v[34:35], v[34:35], v[82:83]
	v_pk_add_f32 v[38:39], v[38:39], v[88:89]
	v_pk_add_f32 v[40:41], v[40:41], v[86:87]
	v_pk_add_f32 v[36:37], v[36:37], v[92:93]
	v_pk_add_f32 v[34:35], v[34:35], v[90:91]
	v_pk_add_f32 v[38:39], v[38:39], v[96:97]
	v_pk_add_f32 v[40:41], v[40:41], v[94:95]
	v_pk_add_f32 v[36:37], v[36:37], v[100:101]
	v_pk_add_f32 v[34:35], v[34:35], v[98:99]
	v_pk_add_f32 v[38:39], v[38:39], v[104:105]
	v_pk_add_f32 v[40:41], v[40:41], v[102:103]
	v_pk_add_f32 v[36:37], v[36:37], v[108:109]
	v_pk_add_f32 v[34:35], v[34:35], v[106:107]
	v_pk_add_f32 v[38:39], v[38:39], v[112:113]
	v_pk_add_f32 v[40:41], v[40:41], v[110:111]
	v_pk_add_f32 v[36:37], v[36:37], v[116:117]
	v_pk_add_f32 v[34:35], v[34:35], v[114:115]
	v_pk_add_f32 v[38:39], v[38:39], v[120:121]
	v_pk_add_f32 v[40:41], v[40:41], v[118:119]
	v_pk_add_f32 v[6:7], v[6:7], v[38:39]
	v_pk_add_f32 v[4:5], v[4:5], v[40:41]
	v_pk_add_f32 v[30:31], v[34:35], v[122:123]
	v_pk_add_f32 v[32:33], v[36:37], v[124:125]
	v_lshl_add_u64 v[34:35], v[16:17], 2, v[12:13]
	v_pk_add_f32 v[0:1], v[0:1], v[30:31]
	v_pk_add_f32 v[2:3], v[2:3], v[32:33]
	global_store_dwordx4 v[34:35], v[4:7], off
	global_store_dwordx4 v[34:35], v[0:3], off offset:16
	v_cvt_pk_bf16_f32 v30, v4, v5
	v_cvt_pk_bf16_f32 v32, v0, v1
	v_mul_f32_e32 v5, v5, v5
	v_mul_f32_e32 v1, v1, v1
	v_fmac_f32_e32 v5, v4, v4
	v_mul_f32_e32 v4, v7, v7
	v_fmac_f32_e32 v1, v0, v0
	v_mul_f32_e32 v0, v3, v3
	v_fmac_f32_e32 v4, v6, v6
	v_fmac_f32_e32 v0, v2, v2
	v_add_f32_e32 v4, v5, v4
	v_add_f32_e32 v0, v1, v0
	v_add_f32_e32 v0, v4, v0
	ds_bpermute_b32 v1, v20, v0
	v_cvt_pk_bf16_f32 v31, v6, v7
	v_cvt_pk_bf16_f32 v33, v2, v3
	v_lshl_add_u64 v[16:17], v[16:17], 1, v[14:15]
	global_store_dwordx4 v[16:17], v[30:33], off
	s_waitcnt lgkmcnt(0)
	v_add_f32_e32 v0, v0, v1
	ds_bpermute_b32 v1, v21, v0
	s_and_b64 exec, exec, s[6:7]
	s_cbranch_execz .LBB0_2262
	v_add_u32_e32 v2, v22, v26
	v_ashrrev_i32_e32 v3, 31, v2
	v_lshl_add_u64 v[2:3], v[2:3], 2, s[10:11]
	s_waitcnt lgkmcnt(0)
	v_add_f32_e32 v0, v0, v1
	global_store_dword v[2:3], v0, off
	s_branch .LBB0_2262
